# same as previous with a much larger spin cap in the 8-block group sync (safety only)
# baseline (speedup 1.0000x reference)
.Lgs6_poll:
	global_load_dword v2, v0, s[6:7] sc1
	s_add_u32 s10, s10, 1
	s_waitcnt vmcnt(0)
	v_readfirstlane_b32 s2, v2
	s_nop 3
	s_cmp_gt_u32 s10, 0x40000
	s_cbranch_scc1 .Lgs6_done
	s_cmp_ge_u32 s2, 8
	s_cbranch_scc1 .Lgs6_done
	s_sleep 1
	s_branch .Lgs6_poll
